# v40: ff2_out weight conversion moved to P10's idle workgroups; ff2_in and w_out conversion in P4 on workgroups 180-255 (two items in flight, non-temporal); P4 last round as half units
# baseline (speedup 1.0000x reference)
.LBB0_774:
	s_abs_i32 s0, s33
	v_cvt_f32_u32_e32 v2, s0
	s_sub_i32 s1, 0, s0
	v_rcp_iflag_f32_e32 v2, v2
	s_nop 0
	v_mul_f32_e32 v2, 0x4f7ffffe, v2
	v_cvt_u32_f32_e32 v2, v2
	s_nop 0
	v_readfirstlane_b32 s2, v2
	s_mul_i32 s1, s1, s2
	s_mul_hi_u32 s1, s2, s1
	s_add_i32 s2, s2, s1
	s_mul_hi_u32 s1, s2, 0x35a
	s_mul_i32 s1, s1, s0
	s_sub_i32 s1, 0x35a, s1
	s_sub_i32 s2, s1, s0
	s_cmp_ge_u32 s1, s0
	s_cselect_b32 s1, s2, s1
	s_sub_i32 s2, s1, s0
	s_cmp_ge_u32 s1, s0
	s_cselect_b32 s0, s2, s1
	s_movk_i32 s0, 180
	s_cmp_ge_i32 s24, s0
	s_cbranch_scc0 .LBB0_796
	s_sub_i32 s1, s24, s0
	s_lshl_b32 s1, s1, 3
	s_add_i32 s6, s1, s83
	s_cmpk_gt_u32 s6, 0x127f
	s_cbranch_scc1 .LBB0_796
	s_cmpk_gt_u32 s6, 3327
	s_cbranch_scc1 .Lcv3_end
	s_sub_i32 s7, s33, s0
	s_lshl_b32 s7, s7, 3
	v_mbcnt_lo_u32_b32 v1, -1, 0
	v_mbcnt_hi_u32_b32 v1, -1, v1
	v_and_b32_e32 v2, 31, v1
	v_lshrrev_b32_e32 v3, 5, v1
	s_mul_i32 s4, s83, 0x4400
	v_mad_u32_u24 v4, v3, 33, v2
	v_lshl_add_u32 v4, v4, 2, s4
	v_and_b32_e32 v5, 7, v1
	v_lshrrev_b32_e32 v6, 3, v1
	v_mul_u32_u24_e32 v7, 0x108, v5
	v_add_u32_e32 v7, v7, v6
	v_lshl_add_u32 v7, v7, 2, s4
.Lcv3_item:
	s_add_i32 s23, s6, s7
	s_cmpk_lt_u32 s23, 3328
	s_cbranch_scc0 .Lcv3_single
	s_cmpk_lt_u32 s6, 2816
	s_cselect_b32 s5, 0, 1408
	s_add_i32 s5, s6, s5
	s_cmpk_lt_u32 s5, 2816
	s_cbranch_scc0 .Lcv3_fo_a
	s_mul_i32 s1, s5, 5958
	s_lshr_b32 s1, s1, 20
	s_mul_i32 s2, s1, 176
	s_sub_i32 s2, s5, s2
	s_lshl_b32 s18, s2, 5
	s_lshl_b32 s17, s1, 6
	s_cmpk_lt_u32 s18, 2816
	s_cselect_b32 s2, 0, 2816
	s_cselect_b32 s3, 0, 128
	s_sub_i32 s2, s18, s2
	s_lshr_b32 s16, s2, 7
	s_lshl_b32 s16, s16, 8
	s_and_b32 s2, s2, 127
	s_add_i32 s16, s16, s2
	s_add_i32 s16, s16, s3
	s_mov_b64 s[10:11], s[40:41]
	s_movk_i32 s12, 5632
	s_movk_i32 s13, 1024
	s_add_u32 s14, s26, 0x1400000
	s_addc_u32 s15, s27, 0
	s_branch .Lcv3_go_a
.Lcv3_fo_a:
	s_cmpk_lt_u32 s5, 4224
	s_cbranch_scc0 .Lcv3_wo_a
	s_sub_i32 s1, s5, 2816
	s_lshr_b32 s2, s1, 5
	s_and_b32 s1, s1, 31
	s_lshl_b32 s18, s1, 5
	s_lshl_b32 s17, s2, 6
	s_mov_b32 s16, s18
	s_mov_b64 s[10:11], s[42:43]
	s_movk_i32 s12, 1024
	s_movk_i32 s13, 2816
	s_add_u32 s14, s26, 0x2000000
	s_addc_u32 s15, s27, 0
	s_branch .Lcv3_go_a
.Lcv3_wo_a:
	s_sub_i32 s1, s5, 4224
	s_lshr_b32 s2, s1, 5
	s_and_b32 s1, s1, 31
	s_lshl_b32 s18, s1, 5
	s_lshl_b32 s17, s2, 6
	s_mov_b32 s16, s18
	s_mov_b64 s[10:11], s[46:47]
	s_movk_i32 s12, 1024
	s_movk_i32 s13, 1024
	s_add_u32 s14, s26, 0x2d00000
	s_addc_u32 s15, s27, 0
.Lcv3_go_a:
	s_mul_i32 s1, s17, s12
	s_add_i32 s1, s1, s18
	s_lshl_b32 s1, s1, 2
	s_add_u32 s10, s10, s1
	s_addc_u32 s11, s11, 0
	v_mul_lo_u32 v8, v3, s12
	v_add_lshl_u32 v8, v8, v2, 2
	s_lshl_b32 s19, s12, 3
	global_load_dword v16, v8, s[10:11] nt
	s_add_u32 s10, s10, s19
	s_addc_u32 s11, s11, 0
	global_load_dword v17, v8, s[10:11] nt
	s_add_u32 s10, s10, s19
	s_addc_u32 s11, s11, 0
	global_load_dword v18, v8, s[10:11] nt
	s_add_u32 s10, s10, s19
	s_addc_u32 s11, s11, 0
	global_load_dword v19, v8, s[10:11] nt
	s_add_u32 s10, s10, s19
	s_addc_u32 s11, s11, 0
	global_load_dword v20, v8, s[10:11] nt
	s_add_u32 s10, s10, s19
	s_addc_u32 s11, s11, 0
	global_load_dword v21, v8, s[10:11] nt
	s_add_u32 s10, s10, s19
	s_addc_u32 s11, s11, 0
	global_load_dword v22, v8, s[10:11] nt
	s_add_u32 s10, s10, s19
	s_addc_u32 s11, s11, 0
	global_load_dword v23, v8, s[10:11] nt
	s_add_u32 s10, s10, s19
	s_addc_u32 s11, s11, 0
	global_load_dword v24, v8, s[10:11] nt
	s_add_u32 s10, s10, s19
	s_addc_u32 s11, s11, 0
	global_load_dword v25, v8, s[10:11] nt
	s_add_u32 s10, s10, s19
	s_addc_u32 s11, s11, 0
	global_load_dword v26, v8, s[10:11] nt
	s_add_u32 s10, s10, s19
	s_addc_u32 s11, s11, 0
	global_load_dword v27, v8, s[10:11] nt
	s_add_u32 s10, s10, s19
	s_addc_u32 s11, s11, 0
	global_load_dword v28, v8, s[10:11] nt
	s_add_u32 s10, s10, s19
	s_addc_u32 s11, s11, 0
	global_load_dword v29, v8, s[10:11] nt
	s_add_u32 s10, s10, s19
	s_addc_u32 s11, s11, 0
	global_load_dword v30, v8, s[10:11] nt
	s_add_u32 s10, s10, s19
	s_addc_u32 s11, s11, 0
	global_load_dword v31, v8, s[10:11] nt
	s_add_u32 s10, s10, s19
	s_addc_u32 s11, s11, 0
	global_load_dword v32, v8, s[10:11] nt
	s_add_u32 s10, s10, s19
	s_addc_u32 s11, s11, 0
	global_load_dword v33, v8, s[10:11] nt
	s_add_u32 s10, s10, s19
	s_addc_u32 s11, s11, 0
	global_load_dword v34, v8, s[10:11] nt
	s_add_u32 s10, s10, s19
	s_addc_u32 s11, s11, 0
	global_load_dword v35, v8, s[10:11] nt
	s_add_u32 s10, s10, s19
	s_addc_u32 s11, s11, 0
	global_load_dword v36, v8, s[10:11] nt
	s_add_u32 s10, s10, s19
	s_addc_u32 s11, s11, 0
	global_load_dword v37, v8, s[10:11] nt
	s_add_u32 s10, s10, s19
	s_addc_u32 s11, s11, 0
	global_load_dword v38, v8, s[10:11] nt
	s_add_u32 s10, s10, s19
	s_addc_u32 s11, s11, 0
	global_load_dword v39, v8, s[10:11] nt
	s_add_u32 s10, s10, s19
	s_addc_u32 s11, s11, 0
	global_load_dword v40, v8, s[10:11] nt
	s_add_u32 s10, s10, s19
	s_addc_u32 s11, s11, 0
	global_load_dword v41, v8, s[10:11] nt
	s_add_u32 s10, s10, s19
	s_addc_u32 s11, s11, 0
	global_load_dword v42, v8, s[10:11] nt
	s_add_u32 s10, s10, s19
	s_addc_u32 s11, s11, 0
	global_load_dword v43, v8, s[10:11] nt
	s_add_u32 s10, s10, s19
	s_addc_u32 s11, s11, 0
	global_load_dword v44, v8, s[10:11] nt
	s_add_u32 s10, s10, s19
	s_addc_u32 s11, s11, 0
	global_load_dword v45, v8, s[10:11] nt
	s_add_u32 s10, s10, s19
	s_addc_u32 s11, s11, 0
	global_load_dword v46, v8, s[10:11] nt
	s_add_u32 s10, s10, s19
	s_addc_u32 s11, s11, 0
	global_load_dword v47, v8, s[10:11] nt
	s_mul_i32 s1, s16, s13
	s_add_i32 s1, s1, s17
	s_lshl_b32 s1, s1, 1
	s_add_u32 s14, s14, s1
	s_addc_u32 s15, s15, 0
	s_mov_b64 s[20:21], s[14:15]
	s_mov_b32 s22, s13
	s_cmpk_lt_u32 s23, 2816
	s_cselect_b32 s5, 0, 1408
	s_add_i32 s5, s23, s5
	s_cmpk_lt_u32 s5, 2816
	s_cbranch_scc0 .Lcv3_fo_b
	s_mul_i32 s1, s5, 5958
	s_lshr_b32 s1, s1, 20
	s_mul_i32 s2, s1, 176
	s_sub_i32 s2, s5, s2
	s_lshl_b32 s18, s2, 5
	s_lshl_b32 s17, s1, 6
	s_cmpk_lt_u32 s18, 2816
	s_cselect_b32 s2, 0, 2816
	s_cselect_b32 s3, 0, 128
	s_sub_i32 s2, s18, s2
	s_lshr_b32 s16, s2, 7
	s_lshl_b32 s16, s16, 8
	s_and_b32 s2, s2, 127
	s_add_i32 s16, s16, s2
	s_add_i32 s16, s16, s3
	s_mov_b64 s[10:11], s[40:41]
	s_movk_i32 s12, 5632
	s_movk_i32 s13, 1024
	s_add_u32 s14, s26, 0x1400000
	s_addc_u32 s15, s27, 0
	s_branch .Lcv3_go_b

.Lcv3_go_b:
	s_mul_i32 s1, s17, s12
	s_add_i32 s1, s1, s18
	s_lshl_b32 s1, s1, 2
	s_add_u32 s10, s10, s1
	s_addc_u32 s11, s11, 0
	v_mul_lo_u32 v8, v3, s12
	v_add_lshl_u32 v8, v8, v2, 2
	s_lshl_b32 s19, s12, 3
	global_load_dword v48, v8, s[10:11] nt
	s_add_u32 s10, s10, s19
	s_addc_u32 s11, s11, 0
	global_load_dword v49, v8, s[10:11] nt
	s_add_u32 s10, s10, s19
	s_addc_u32 s11, s11, 0
	global_load_dword v50, v8, s[10:11] nt
	s_add_u32 s10, s10, s19
	s_addc_u32 s11, s11, 0
	global_load_dword v51, v8, s[10:11] nt
	s_add_u32 s10, s10, s19
	s_addc_u32 s11, s11, 0
	global_load_dword v52, v8, s[10:11] nt
	s_add_u32 s10, s10, s19
	s_addc_u32 s11, s11, 0
	global_load_dword v53, v8, s[10:11] nt
	s_add_u32 s10, s10, s19
	s_addc_u32 s11, s11, 0
	global_load_dword v54, v8, s[10:11] nt
	s_add_u32 s10, s10, s19
	s_addc_u32 s11, s11, 0
	global_load_dword v55, v8, s[10:11] nt
	s_add_u32 s10, s10, s19
	s_addc_u32 s11, s11, 0
	global_load_dword v56, v8, s[10:11] nt
	s_add_u32 s10, s10, s19
	s_addc_u32 s11, s11, 0
	global_load_dword v57, v8, s[10:11] nt
	s_add_u32 s10, s10, s19
	s_addc_u32 s11, s11, 0
	global_load_dword v58, v8, s[10:11] nt
	s_add_u32 s10, s10, s19
	s_addc_u32 s11, s11, 0
	global_load_dword v59, v8, s[10:11] nt
	s_add_u32 s10, s10, s19
	s_addc_u32 s11, s11, 0
	global_load_dword v60, v8, s[10:11] nt
	s_add_u32 s10, s10, s19
	s_addc_u32 s11, s11, 0
	global_load_dword v61, v8, s[10:11] nt
	s_add_u32 s10, s10, s19
	s_addc_u32 s11, s11, 0
	global_load_dword v62, v8, s[10:11] nt
	s_add_u32 s10, s10, s19
	s_addc_u32 s11, s11, 0
	global_load_dword v63, v8, s[10:11] nt
	s_add_u32 s10, s10, s19
	s_addc_u32 s11, s11, 0
	global_load_dword v64, v8, s[10:11] nt
	s_add_u32 s10, s10, s19
	s_addc_u32 s11, s11, 0
	global_load_dword v65, v8, s[10:11] nt
	s_add_u32 s10, s10, s19
	s_addc_u32 s11, s11, 0
	global_load_dword v66, v8, s[10:11] nt
	s_add_u32 s10, s10, s19
	s_addc_u32 s11, s11, 0
	global_load_dword v67, v8, s[10:11] nt
	s_add_u32 s10, s10, s19
	s_addc_u32 s11, s11, 0
	global_load_dword v68, v8, s[10:11] nt
	s_add_u32 s10, s10, s19
	s_addc_u32 s11, s11, 0
	global_load_dword v69, v8, s[10:11] nt
	s_add_u32 s10, s10, s19
	s_addc_u32 s11, s11, 0
	global_load_dword v70, v8, s[10:11] nt
	s_add_u32 s10, s10, s19
	s_addc_u32 s11, s11, 0
	global_load_dword v71, v8, s[10:11] nt
	s_add_u32 s10, s10, s19
	s_addc_u32 s11, s11, 0
	global_load_dword v72, v8, s[10:11] nt
	s_add_u32 s10, s10, s19
	s_addc_u32 s11, s11, 0
	global_load_dword v73, v8, s[10:11] nt
	s_add_u32 s10, s10, s19
	s_addc_u32 s11, s11, 0
	global_load_dword v74, v8, s[10:11] nt
	s_add_u32 s10, s10, s19
	s_addc_u32 s11, s11, 0
	global_load_dword v75, v8, s[10:11] nt
	s_add_u32 s10, s10, s19
	s_addc_u32 s11, s11, 0
	global_load_dword v76, v8, s[10:11] nt
	s_add_u32 s10, s10, s19
	s_addc_u32 s11, s11, 0
	global_load_dword v77, v8, s[10:11] nt
	s_add_u32 s10, s10, s19
	s_addc_u32 s11, s11, 0
	global_load_dword v78, v8, s[10:11] nt
	s_add_u32 s10, s10, s19
	s_addc_u32 s11, s11, 0
	global_load_dword v79, v8, s[10:11] nt
	s_mul_i32 s1, s16, s13
	s_add_i32 s1, s1, s17
	s_lshl_b32 s1, s1, 1
	s_add_u32 s14, s14, s1
	s_addc_u32 s15, s15, 0
	s_waitcnt vmcnt(63)
	ds_write_b32 v4, v16 offset:0
	s_waitcnt vmcnt(62)
	ds_write_b32 v4, v17 offset:264
	s_waitcnt vmcnt(61)
	ds_write_b32 v4, v18 offset:528
	s_waitcnt vmcnt(60)
	ds_write_b32 v4, v19 offset:792
	s_waitcnt vmcnt(59)
	ds_write_b32 v4, v20 offset:1056
	s_waitcnt vmcnt(58)
	ds_write_b32 v4, v21 offset:1320
	s_waitcnt vmcnt(57)
	ds_write_b32 v4, v22 offset:1584
	s_waitcnt vmcnt(56)
	ds_write_b32 v4, v23 offset:1848
	s_waitcnt vmcnt(55)
	ds_write_b32 v4, v24 offset:2112
	s_waitcnt vmcnt(54)
	ds_write_b32 v4, v25 offset:2376
	s_waitcnt vmcnt(53)
	ds_write_b32 v4, v26 offset:2640
	s_waitcnt vmcnt(52)
	ds_write_b32 v4, v27 offset:2904
	s_waitcnt vmcnt(51)
	ds_write_b32 v4, v28 offset:3168
	s_waitcnt vmcnt(50)
	ds_write_b32 v4, v29 offset:3432
	s_waitcnt vmcnt(49)
	ds_write_b32 v4, v30 offset:3696
	s_waitcnt vmcnt(48)
	ds_write_b32 v4, v31 offset:3960
	s_waitcnt vmcnt(47)
	ds_write_b32 v4, v32 offset:4224
	s_waitcnt vmcnt(46)
	ds_write_b32 v4, v33 offset:4488
	s_waitcnt vmcnt(45)
	ds_write_b32 v4, v34 offset:4752
	s_waitcnt vmcnt(44)
	ds_write_b32 v4, v35 offset:5016
	s_waitcnt vmcnt(43)
	ds_write_b32 v4, v36 offset:5280
	s_waitcnt vmcnt(42)
	ds_write_b32 v4, v37 offset:5544
	s_waitcnt vmcnt(41)
	ds_write_b32 v4, v38 offset:5808
	s_waitcnt vmcnt(40)
	ds_write_b32 v4, v39 offset:6072
	s_waitcnt vmcnt(39)
	ds_write_b32 v4, v40 offset:6336
	s_waitcnt vmcnt(38)
	ds_write_b32 v4, v41 offset:6600
	s_waitcnt vmcnt(37)
	ds_write_b32 v4, v42 offset:6864
	s_waitcnt vmcnt(36)
	ds_write_b32 v4, v43 offset:7128
	s_waitcnt vmcnt(35)
	ds_write_b32 v4, v44 offset:7392
	s_waitcnt vmcnt(34)
	ds_write_b32 v4, v45 offset:7656
	s_waitcnt vmcnt(33)
	ds_write_b32 v4, v46 offset:7920
	s_waitcnt vmcnt(32)
	ds_write_b32 v4, v47 offset:8184
	s_waitcnt vmcnt(31)
	ds_write_b32 v4, v48 offset:8448
	s_waitcnt vmcnt(30)
	ds_write_b32 v4, v49 offset:8712
	s_waitcnt vmcnt(29)
	ds_write_b32 v4, v50 offset:8976
	s_waitcnt vmcnt(28)
	ds_write_b32 v4, v51 offset:9240
	s_waitcnt vmcnt(27)
	ds_write_b32 v4, v52 offset:9504
	s_waitcnt vmcnt(26)
	ds_write_b32 v4, v53 offset:9768
	s_waitcnt vmcnt(25)
	ds_write_b32 v4, v54 offset:10032
	s_waitcnt vmcnt(24)
	ds_write_b32 v4, v55 offset:10296
	s_waitcnt vmcnt(23)
	ds_write_b32 v4, v56 offset:10560
	s_waitcnt vmcnt(22)
	ds_write_b32 v4, v57 offset:10824
	s_waitcnt vmcnt(21)
	ds_write_b32 v4, v58 offset:11088
	s_waitcnt vmcnt(20)
	ds_write_b32 v4, v59 offset:11352
	s_waitcnt vmcnt(19)
	ds_write_b32 v4, v60 offset:11616
	s_waitcnt vmcnt(18)
	ds_write_b32 v4, v61 offset:11880
	s_waitcnt vmcnt(17)
	ds_write_b32 v4, v62 offset:12144
	s_waitcnt vmcnt(16)
	ds_write_b32 v4, v63 offset:12408
	s_waitcnt vmcnt(15)
	ds_write_b32 v4, v64 offset:12672
	s_waitcnt vmcnt(14)
	ds_write_b32 v4, v65 offset:12936
	s_waitcnt vmcnt(13)
	ds_write_b32 v4, v66 offset:13200
	s_waitcnt vmcnt(12)
	ds_write_b32 v4, v67 offset:13464
	s_waitcnt vmcnt(11)
	ds_write_b32 v4, v68 offset:13728
	s_waitcnt vmcnt(10)
	ds_write_b32 v4, v69 offset:13992
	s_waitcnt vmcnt(9)
	ds_write_b32 v4, v70 offset:14256
	s_waitcnt vmcnt(8)
	ds_write_b32 v4, v71 offset:14520
	s_waitcnt vmcnt(7)
	ds_write_b32 v4, v72 offset:14784
	s_waitcnt vmcnt(6)
	ds_write_b32 v4, v73 offset:15048
	s_waitcnt vmcnt(5)
	ds_write_b32 v4, v74 offset:15312
	s_waitcnt vmcnt(4)
	ds_write_b32 v4, v75 offset:15576
	s_waitcnt vmcnt(3)
	ds_write_b32 v4, v76 offset:15840
	s_waitcnt vmcnt(2)
	ds_write_b32 v4, v77 offset:16104
	s_waitcnt vmcnt(1)
	ds_write_b32 v4, v78 offset:16368
	s_waitcnt vmcnt(0)
	ds_write_b32 v4, v79 offset:16632
	s_waitcnt lgkmcnt(0)
	v_mul_lo_u32 v9, v6, s22
	v_lshl_add_u32 v96, v5, 3, v9
	v_lshlrev_b32_e32 v9, 1, v96
	s_lshl_b32 s19, s22, 4
	ds_read_b32 v112, v7 offset:0
	ds_read_b32 v113, v7 offset:132
	ds_read_b32 v114, v7 offset:264
	ds_read_b32 v115, v7 offset:396
	ds_read_b32 v116, v7 offset:528
	ds_read_b32 v117, v7 offset:660
	ds_read_b32 v118, v7 offset:792
	ds_read_b32 v119, v7 offset:924
	s_waitcnt lgkmcnt(0)
	v_cvt_pk_bf16_f32 v96, v112, v113
	v_cvt_pk_bf16_f32 v97, v114, v115
	v_cvt_pk_bf16_f32 v98, v116, v117
	v_cvt_pk_bf16_f32 v99, v118, v119
	global_store_dwordx4 v9, v[96:99], s[20:21] nt
	s_add_u32 s20, s20, s19
	s_addc_u32 s21, s21, 0
	ds_read_b32 v120, v7 offset:32
	ds_read_b32 v121, v7 offset:164
	ds_read_b32 v122, v7 offset:296
	ds_read_b32 v123, v7 offset:428
	ds_read_b32 v124, v7 offset:560
	ds_read_b32 v125, v7 offset:692
	ds_read_b32 v126, v7 offset:824
	ds_read_b32 v127, v7 offset:956
	s_waitcnt lgkmcnt(0)
	v_cvt_pk_bf16_f32 v100, v120, v121
	v_cvt_pk_bf16_f32 v101, v122, v123
	v_cvt_pk_bf16_f32 v102, v124, v125
	v_cvt_pk_bf16_f32 v103, v126, v127
	global_store_dwordx4 v9, v[100:103], s[20:21] nt
	s_add_u32 s20, s20, s19
	s_addc_u32 s21, s21, 0
	ds_read_b32 v128, v7 offset:64
	ds_read_b32 v129, v7 offset:196
	ds_read_b32 v130, v7 offset:328
	ds_read_b32 v131, v7 offset:460
	ds_read_b32 v132, v7 offset:592
	ds_read_b32 v133, v7 offset:724
	ds_read_b32 v134, v7 offset:856
	ds_read_b32 v135, v7 offset:988
	s_waitcnt lgkmcnt(0)
	v_cvt_pk_bf16_f32 v104, v128, v129
	v_cvt_pk_bf16_f32 v105, v130, v131
	v_cvt_pk_bf16_f32 v106, v132, v133
	v_cvt_pk_bf16_f32 v107, v134, v135
	global_store_dwordx4 v9, v[104:107], s[20:21] nt
	s_add_u32 s20, s20, s19
	s_addc_u32 s21, s21, 0
	ds_read_b32 v136, v7 offset:96
	ds_read_b32 v137, v7 offset:228
	ds_read_b32 v138, v7 offset:360
	ds_read_b32 v139, v7 offset:492
	ds_read_b32 v140, v7 offset:624
	ds_read_b32 v141, v7 offset:756
	ds_read_b32 v142, v7 offset:888
	ds_read_b32 v143, v7 offset:1020
	s_waitcnt lgkmcnt(0)
	v_cvt_pk_bf16_f32 v108, v136, v137
	v_cvt_pk_bf16_f32 v109, v138, v139
	v_cvt_pk_bf16_f32 v110, v140, v141
	v_cvt_pk_bf16_f32 v111, v142, v143
	global_store_dwordx4 v9, v[108:111], s[20:21] nt
	v_mul_lo_u32 v9, v6, s13
	v_lshl_add_u32 v96, v5, 3, v9
	v_lshlrev_b32_e32 v9, 1, v96
	s_lshl_b32 s19, s13, 4
	ds_read_b32 v112, v7 offset:8448
	ds_read_b32 v113, v7 offset:8580
	ds_read_b32 v114, v7 offset:8712
	ds_read_b32 v115, v7 offset:8844
	ds_read_b32 v116, v7 offset:8976
	ds_read_b32 v117, v7 offset:9108
	ds_read_b32 v118, v7 offset:9240
	ds_read_b32 v119, v7 offset:9372
	s_waitcnt lgkmcnt(0)
	v_cvt_pk_bf16_f32 v96, v112, v113
	v_cvt_pk_bf16_f32 v97, v114, v115
	v_cvt_pk_bf16_f32 v98, v116, v117
	v_cvt_pk_bf16_f32 v99, v118, v119
	global_store_dwordx4 v9, v[96:99], s[14:15] nt
	s_add_u32 s14, s14, s19
	s_addc_u32 s15, s15, 0
	ds_read_b32 v120, v7 offset:8480
	ds_read_b32 v121, v7 offset:8612
	ds_read_b32 v122, v7 offset:8744
	ds_read_b32 v123, v7 offset:8876
	ds_read_b32 v124, v7 offset:9008
	ds_read_b32 v125, v7 offset:9140
	ds_read_b32 v126, v7 offset:9272
	ds_read_b32 v127, v7 offset:9404
	s_waitcnt lgkmcnt(0)
	v_cvt_pk_bf16_f32 v100, v120, v121
	v_cvt_pk_bf16_f32 v101, v122, v123
	v_cvt_pk_bf16_f32 v102, v124, v125
	v_cvt_pk_bf16_f32 v103, v126, v127
	global_store_dwordx4 v9, v[100:103], s[14:15] nt
	s_add_u32 s14, s14, s19
	s_addc_u32 s15, s15, 0
	ds_read_b32 v128, v7 offset:8512
	ds_read_b32 v129, v7 offset:8644
	ds_read_b32 v130, v7 offset:8776
	ds_read_b32 v131, v7 offset:8908
	ds_read_b32 v132, v7 offset:9040
	ds_read_b32 v133, v7 offset:9172
	ds_read_b32 v134, v7 offset:9304
	ds_read_b32 v135, v7 offset:9436
	s_waitcnt lgkmcnt(0)
	v_cvt_pk_bf16_f32 v104, v128, v129
	v_cvt_pk_bf16_f32 v105, v130, v131
	v_cvt_pk_bf16_f32 v106, v132, v133
	v_cvt_pk_bf16_f32 v107, v134, v135
	global_store_dwordx4 v9, v[104:107], s[14:15] nt
	s_add_u32 s14, s14, s19
	s_addc_u32 s15, s15, 0
	ds_read_b32 v136, v7 offset:8544
	ds_read_b32 v137, v7 offset:8676
	ds_read_b32 v138, v7 offset:8808
	ds_read_b32 v139, v7 offset:8940
	ds_read_b32 v140, v7 offset:9072
	ds_read_b32 v141, v7 offset:9204
	ds_read_b32 v142, v7 offset:9336
	ds_read_b32 v143, v7 offset:9468
	s_waitcnt lgkmcnt(0)
	v_cvt_pk_bf16_f32 v108, v136, v137
	v_cvt_pk_bf16_f32 v109, v138, v139
	v_cvt_pk_bf16_f32 v110, v140, v141
	v_cvt_pk_bf16_f32 v111, v142, v143
	global_store_dwordx4 v9, v[108:111], s[14:15] nt
	s_add_i32 s6, s23, s7
	s_cmpk_lt_u32 s6, 3328
	s_cbranch_scc1 .Lcv3_item
	s_branch .Lcv3_end
.Lcv3_single:
	s_cmpk_lt_u32 s6, 2816
	s_cselect_b32 s5, 0, 1408
	s_add_i32 s5, s6, s5
	s_cmpk_lt_u32 s5, 2816
	s_cbranch_scc0 .Lcv3_fo_s
	s_mul_i32 s1, s5, 5958
	s_lshr_b32 s1, s1, 20
	s_mul_i32 s2, s1, 176
	s_sub_i32 s2, s5, s2
	s_lshl_b32 s18, s2, 5
	s_lshl_b32 s17, s1, 6
	s_cmpk_lt_u32 s18, 2816
	s_cselect_b32 s2, 0, 2816
	s_cselect_b32 s3, 0, 128
	s_sub_i32 s2, s18, s2
	s_lshr_b32 s16, s2, 7
	s_lshl_b32 s16, s16, 8
	s_and_b32 s2, s2, 127
	s_add_i32 s16, s16, s2
	s_add_i32 s16, s16, s3
	s_mov_b64 s[10:11], s[40:41]
	s_movk_i32 s12, 5632
	s_movk_i32 s13, 1024
	s_add_u32 s14, s26, 0x1400000
	s_addc_u32 s15, s27, 0
	s_branch .Lcv3_go_s

.LBB0_1706:
	s_cmp_gt_i32 s91, 11
	s_cbranch_scc0 .LBB0_1760
	s_cmpk_lt_u32 s24, 172
	s_cbranch_scc1 .Lcvp10_end
	v_readlane_b32 s42, v255, 46
	v_readlane_b32 s43, v255, 47
	s_sub_i32 s1, s24, 172
	s_lshl_b32 s1, s1, 3
	s_add_i32 s6, s1, s83
	s_addk_i32 s6, 2816
	s_movk_i32 s0, 172
	s_cmpk_gt_u32 s6, 4223
	s_cbranch_scc1 .Lcvp10_end
	s_sub_i32 s7, s33, s0
	s_lshl_b32 s7, s7, 3
	v_mbcnt_lo_u32_b32 v1, -1, 0
	v_mbcnt_hi_u32_b32 v1, -1, v1
	v_and_b32_e32 v2, 31, v1
	v_lshrrev_b32_e32 v3, 5, v1
	s_mul_i32 s4, s83, 0x4400
	v_mad_u32_u24 v4, v3, 33, v2
	v_lshl_add_u32 v4, v4, 2, s4
	v_and_b32_e32 v5, 7, v1
	v_lshrrev_b32_e32 v6, 3, v1
	v_mul_u32_u24_e32 v7, 0x108, v5
	v_add_u32_e32 v7, v7, v6
	v_lshl_add_u32 v7, v7, 2, s4
.Lcvp10_item:
	s_add_i32 s23, s6, s7
	s_cmpk_lt_u32 s23, 4224
	s_cbranch_scc0 .Lcvp10_single
	s_cmpk_lt_u32 s6, 2816
	s_cbranch_scc0 .Lcvp10_fo_a
	s_mul_i32 s1, s6, 5958
	s_lshr_b32 s1, s1, 20
	s_mul_i32 s2, s1, 176
	s_sub_i32 s2, s6, s2
	s_lshl_b32 s18, s2, 5
	s_lshl_b32 s17, s1, 6
	s_cmpk_lt_u32 s18, 2816
	s_cselect_b32 s2, 0, 2816
	s_cselect_b32 s3, 0, 128
	s_sub_i32 s2, s18, s2
	s_lshr_b32 s16, s2, 7
	s_lshl_b32 s16, s16, 8
	s_and_b32 s2, s2, 127
	s_add_i32 s16, s16, s2
	s_add_i32 s16, s16, s3
	s_mov_b64 s[10:11], s[40:41]
	s_movk_i32 s12, 5632
	s_movk_i32 s13, 1024
	s_add_u32 s14, s26, 0x1400000
	s_addc_u32 s15, s27, 0
	s_branch .Lcvp10_go_a

.Lcvp10_go_b:
	s_mul_i32 s1, s17, s12
	s_add_i32 s1, s1, s18
	s_lshl_b32 s1, s1, 2
	s_add_u32 s10, s10, s1
	s_addc_u32 s11, s11, 0
	v_mul_lo_u32 v8, v3, s12
	v_add_lshl_u32 v8, v8, v2, 2
	s_lshl_b32 s19, s12, 3
	global_load_dword v48, v8, s[10:11] nt
	s_add_u32 s10, s10, s19
	s_addc_u32 s11, s11, 0
	global_load_dword v49, v8, s[10:11] nt
	s_add_u32 s10, s10, s19
	s_addc_u32 s11, s11, 0
	global_load_dword v50, v8, s[10:11] nt
	s_add_u32 s10, s10, s19
	s_addc_u32 s11, s11, 0
	global_load_dword v51, v8, s[10:11] nt
	s_add_u32 s10, s10, s19
	s_addc_u32 s11, s11, 0
	global_load_dword v52, v8, s[10:11] nt
	s_add_u32 s10, s10, s19
	s_addc_u32 s11, s11, 0
	global_load_dword v53, v8, s[10:11] nt
	s_add_u32 s10, s10, s19
	s_addc_u32 s11, s11, 0
	global_load_dword v54, v8, s[10:11] nt
	s_add_u32 s10, s10, s19
	s_addc_u32 s11, s11, 0
	global_load_dword v55, v8, s[10:11] nt
	s_add_u32 s10, s10, s19
	s_addc_u32 s11, s11, 0
	global_load_dword v56, v8, s[10:11] nt
	s_add_u32 s10, s10, s19
	s_addc_u32 s11, s11, 0
	global_load_dword v57, v8, s[10:11] nt
	s_add_u32 s10, s10, s19
	s_addc_u32 s11, s11, 0
	global_load_dword v58, v8, s[10:11] nt
	s_add_u32 s10, s10, s19
	s_addc_u32 s11, s11, 0
	global_load_dword v59, v8, s[10:11] nt
	s_add_u32 s10, s10, s19
	s_addc_u32 s11, s11, 0
	global_load_dword v60, v8, s[10:11] nt
	s_add_u32 s10, s10, s19
	s_addc_u32 s11, s11, 0
	global_load_dword v61, v8, s[10:11] nt
	s_add_u32 s10, s10, s19
	s_addc_u32 s11, s11, 0
	global_load_dword v62, v8, s[10:11] nt
	s_add_u32 s10, s10, s19
	s_addc_u32 s11, s11, 0
	global_load_dword v63, v8, s[10:11] nt
	s_add_u32 s10, s10, s19
	s_addc_u32 s11, s11, 0
	global_load_dword v64, v8, s[10:11] nt
	s_add_u32 s10, s10, s19
	s_addc_u32 s11, s11, 0
	global_load_dword v65, v8, s[10:11] nt
	s_add_u32 s10, s10, s19
	s_addc_u32 s11, s11, 0
	global_load_dword v66, v8, s[10:11] nt
	s_add_u32 s10, s10, s19
	s_addc_u32 s11, s11, 0
	global_load_dword v67, v8, s[10:11] nt
	s_add_u32 s10, s10, s19
	s_addc_u32 s11, s11, 0
	global_load_dword v68, v8, s[10:11] nt
	s_add_u32 s10, s10, s19
	s_addc_u32 s11, s11, 0
	global_load_dword v69, v8, s[10:11] nt
	s_add_u32 s10, s10, s19
	s_addc_u32 s11, s11, 0
	global_load_dword v70, v8, s[10:11] nt
	s_add_u32 s10, s10, s19
	s_addc_u32 s11, s11, 0
	global_load_dword v71, v8, s[10:11] nt
	s_add_u32 s10, s10, s19
	s_addc_u32 s11, s11, 0
	global_load_dword v72, v8, s[10:11] nt
	s_add_u32 s10, s10, s19
	s_addc_u32 s11, s11, 0
	global_load_dword v73, v8, s[10:11] nt
	s_add_u32 s10, s10, s19
	s_addc_u32 s11, s11, 0
	global_load_dword v74, v8, s[10:11] nt
	s_add_u32 s10, s10, s19
	s_addc_u32 s11, s11, 0
	global_load_dword v75, v8, s[10:11] nt
	s_add_u32 s10, s10, s19
	s_addc_u32 s11, s11, 0
	global_load_dword v76, v8, s[10:11] nt
	s_add_u32 s10, s10, s19
	s_addc_u32 s11, s11, 0
	global_load_dword v77, v8, s[10:11] nt
	s_add_u32 s10, s10, s19
	s_addc_u32 s11, s11, 0
	global_load_dword v78, v8, s[10:11] nt
	s_add_u32 s10, s10, s19
	s_addc_u32 s11, s11, 0
	global_load_dword v79, v8, s[10:11] nt
	s_mul_i32 s1, s16, s13
	s_add_i32 s1, s1, s17
	s_lshl_b32 s1, s1, 1
	s_add_u32 s14, s14, s1
	s_addc_u32 s15, s15, 0
	s_waitcnt vmcnt(63)
	ds_write_b32 v4, v16 offset:0
	s_waitcnt vmcnt(62)
	ds_write_b32 v4, v17 offset:264
	s_waitcnt vmcnt(61)
	ds_write_b32 v4, v18 offset:528
	s_waitcnt vmcnt(60)
	ds_write_b32 v4, v19 offset:792
	s_waitcnt vmcnt(59)
	ds_write_b32 v4, v20 offset:1056
	s_waitcnt vmcnt(58)
	ds_write_b32 v4, v21 offset:1320
	s_waitcnt vmcnt(57)
	ds_write_b32 v4, v22 offset:1584
	s_waitcnt vmcnt(56)
	ds_write_b32 v4, v23 offset:1848
	s_waitcnt vmcnt(55)
	ds_write_b32 v4, v24 offset:2112
	s_waitcnt vmcnt(54)
	ds_write_b32 v4, v25 offset:2376
	s_waitcnt vmcnt(53)
	ds_write_b32 v4, v26 offset:2640
	s_waitcnt vmcnt(52)
	ds_write_b32 v4, v27 offset:2904
	s_waitcnt vmcnt(51)
	ds_write_b32 v4, v28 offset:3168
	s_waitcnt vmcnt(50)
	ds_write_b32 v4, v29 offset:3432
	s_waitcnt vmcnt(49)
	ds_write_b32 v4, v30 offset:3696
	s_waitcnt vmcnt(48)
	ds_write_b32 v4, v31 offset:3960
	s_waitcnt vmcnt(47)
	ds_write_b32 v4, v32 offset:4224
	s_waitcnt vmcnt(46)
	ds_write_b32 v4, v33 offset:4488
	s_waitcnt vmcnt(45)
	ds_write_b32 v4, v34 offset:4752
	s_waitcnt vmcnt(44)
	ds_write_b32 v4, v35 offset:5016
	s_waitcnt vmcnt(43)
	ds_write_b32 v4, v36 offset:5280
	s_waitcnt vmcnt(42)
	ds_write_b32 v4, v37 offset:5544
	s_waitcnt vmcnt(41)
	ds_write_b32 v4, v38 offset:5808
	s_waitcnt vmcnt(40)
	ds_write_b32 v4, v39 offset:6072
	s_waitcnt vmcnt(39)
	ds_write_b32 v4, v40 offset:6336
	s_waitcnt vmcnt(38)
	ds_write_b32 v4, v41 offset:6600
	s_waitcnt vmcnt(37)
	ds_write_b32 v4, v42 offset:6864
	s_waitcnt vmcnt(36)
	ds_write_b32 v4, v43 offset:7128
	s_waitcnt vmcnt(35)
	ds_write_b32 v4, v44 offset:7392
	s_waitcnt vmcnt(34)
	ds_write_b32 v4, v45 offset:7656
	s_waitcnt vmcnt(33)
	ds_write_b32 v4, v46 offset:7920
	s_waitcnt vmcnt(32)
	ds_write_b32 v4, v47 offset:8184
	s_waitcnt vmcnt(31)
	ds_write_b32 v4, v48 offset:8448
	s_waitcnt vmcnt(30)
	ds_write_b32 v4, v49 offset:8712
	s_waitcnt vmcnt(29)
	ds_write_b32 v4, v50 offset:8976
	s_waitcnt vmcnt(28)
	ds_write_b32 v4, v51 offset:9240
	s_waitcnt vmcnt(27)
	ds_write_b32 v4, v52 offset:9504
	s_waitcnt vmcnt(26)
	ds_write_b32 v4, v53 offset:9768
	s_waitcnt vmcnt(25)
	ds_write_b32 v4, v54 offset:10032
	s_waitcnt vmcnt(24)
	ds_write_b32 v4, v55 offset:10296
	s_waitcnt vmcnt(23)
	ds_write_b32 v4, v56 offset:10560
	s_waitcnt vmcnt(22)
	ds_write_b32 v4, v57 offset:10824
	s_waitcnt vmcnt(21)
	ds_write_b32 v4, v58 offset:11088
	s_waitcnt vmcnt(20)
	ds_write_b32 v4, v59 offset:11352
	s_waitcnt vmcnt(19)
	ds_write_b32 v4, v60 offset:11616
	s_waitcnt vmcnt(18)
	ds_write_b32 v4, v61 offset:11880
	s_waitcnt vmcnt(17)
	ds_write_b32 v4, v62 offset:12144
	s_waitcnt vmcnt(16)
	ds_write_b32 v4, v63 offset:12408
	s_waitcnt vmcnt(15)
	ds_write_b32 v4, v64 offset:12672
	s_waitcnt vmcnt(14)
	ds_write_b32 v4, v65 offset:12936
	s_waitcnt vmcnt(13)
	ds_write_b32 v4, v66 offset:13200
	s_waitcnt vmcnt(12)
	ds_write_b32 v4, v67 offset:13464
	s_waitcnt vmcnt(11)
	ds_write_b32 v4, v68 offset:13728
	s_waitcnt vmcnt(10)
	ds_write_b32 v4, v69 offset:13992
	s_waitcnt vmcnt(9)
	ds_write_b32 v4, v70 offset:14256
	s_waitcnt vmcnt(8)
	ds_write_b32 v4, v71 offset:14520
	s_waitcnt vmcnt(7)
	ds_write_b32 v4, v72 offset:14784
	s_waitcnt vmcnt(6)
	ds_write_b32 v4, v73 offset:15048
	s_waitcnt vmcnt(5)
	ds_write_b32 v4, v74 offset:15312
	s_waitcnt vmcnt(4)
	ds_write_b32 v4, v75 offset:15576
	s_waitcnt vmcnt(3)
	ds_write_b32 v4, v76 offset:15840
	s_waitcnt vmcnt(2)
	ds_write_b32 v4, v77 offset:16104
	s_waitcnt vmcnt(1)
	ds_write_b32 v4, v78 offset:16368
	s_waitcnt vmcnt(0)
	ds_write_b32 v4, v79 offset:16632
	s_waitcnt lgkmcnt(0)
	v_mul_lo_u32 v9, v6, s22
	v_lshl_add_u32 v96, v5, 3, v9
	v_lshlrev_b32_e32 v9, 1, v96
	s_lshl_b32 s19, s22, 4
	ds_read_b32 v112, v7 offset:0
	ds_read_b32 v113, v7 offset:132
	ds_read_b32 v114, v7 offset:264
	ds_read_b32 v115, v7 offset:396
	ds_read_b32 v116, v7 offset:528
	ds_read_b32 v117, v7 offset:660
	ds_read_b32 v118, v7 offset:792
	ds_read_b32 v119, v7 offset:924
	s_waitcnt lgkmcnt(0)
	v_cvt_pk_bf16_f32 v96, v112, v113
	v_cvt_pk_bf16_f32 v97, v114, v115
	v_cvt_pk_bf16_f32 v98, v116, v117
	v_cvt_pk_bf16_f32 v99, v118, v119
	global_store_dwordx4 v9, v[96:99], s[20:21] nt
	s_add_u32 s20, s20, s19
	s_addc_u32 s21, s21, 0
	ds_read_b32 v120, v7 offset:32
	ds_read_b32 v121, v7 offset:164
	ds_read_b32 v122, v7 offset:296
	ds_read_b32 v123, v7 offset:428
	ds_read_b32 v124, v7 offset:560
	ds_read_b32 v125, v7 offset:692
	ds_read_b32 v126, v7 offset:824
	ds_read_b32 v127, v7 offset:956
	s_waitcnt lgkmcnt(0)
	v_cvt_pk_bf16_f32 v100, v120, v121
	v_cvt_pk_bf16_f32 v101, v122, v123
	v_cvt_pk_bf16_f32 v102, v124, v125
	v_cvt_pk_bf16_f32 v103, v126, v127
	global_store_dwordx4 v9, v[100:103], s[20:21] nt
	s_add_u32 s20, s20, s19
	s_addc_u32 s21, s21, 0
	ds_read_b32 v128, v7 offset:64
	ds_read_b32 v129, v7 offset:196
	ds_read_b32 v130, v7 offset:328
	ds_read_b32 v131, v7 offset:460
	ds_read_b32 v132, v7 offset:592
	ds_read_b32 v133, v7 offset:724
	ds_read_b32 v134, v7 offset:856
	ds_read_b32 v135, v7 offset:988
	s_waitcnt lgkmcnt(0)
	v_cvt_pk_bf16_f32 v104, v128, v129
	v_cvt_pk_bf16_f32 v105, v130, v131
	v_cvt_pk_bf16_f32 v106, v132, v133
	v_cvt_pk_bf16_f32 v107, v134, v135
	global_store_dwordx4 v9, v[104:107], s[20:21] nt
	s_add_u32 s20, s20, s19
	s_addc_u32 s21, s21, 0
	ds_read_b32 v136, v7 offset:96
	ds_read_b32 v137, v7 offset:228
	ds_read_b32 v138, v7 offset:360
	ds_read_b32 v139, v7 offset:492
	ds_read_b32 v140, v7 offset:624
	ds_read_b32 v141, v7 offset:756
	ds_read_b32 v142, v7 offset:888
	ds_read_b32 v143, v7 offset:1020
	s_waitcnt lgkmcnt(0)
	v_cvt_pk_bf16_f32 v108, v136, v137
	v_cvt_pk_bf16_f32 v109, v138, v139
	v_cvt_pk_bf16_f32 v110, v140, v141
	v_cvt_pk_bf16_f32 v111, v142, v143
	global_store_dwordx4 v9, v[108:111], s[20:21] nt
	v_mul_lo_u32 v9, v6, s13
	v_lshl_add_u32 v96, v5, 3, v9
	v_lshlrev_b32_e32 v9, 1, v96
	s_lshl_b32 s19, s13, 4
	ds_read_b32 v112, v7 offset:8448
	ds_read_b32 v113, v7 offset:8580
	ds_read_b32 v114, v7 offset:8712
	ds_read_b32 v115, v7 offset:8844
	ds_read_b32 v116, v7 offset:8976
	ds_read_b32 v117, v7 offset:9108
	ds_read_b32 v118, v7 offset:9240
	ds_read_b32 v119, v7 offset:9372
	s_waitcnt lgkmcnt(0)
	v_cvt_pk_bf16_f32 v96, v112, v113
	v_cvt_pk_bf16_f32 v97, v114, v115
	v_cvt_pk_bf16_f32 v98, v116, v117
	v_cvt_pk_bf16_f32 v99, v118, v119
	global_store_dwordx4 v9, v[96:99], s[14:15] nt
	s_add_u32 s14, s14, s19
	s_addc_u32 s15, s15, 0
	ds_read_b32 v120, v7 offset:8480
	ds_read_b32 v121, v7 offset:8612
	ds_read_b32 v122, v7 offset:8744
	ds_read_b32 v123, v7 offset:8876
	ds_read_b32 v124, v7 offset:9008
	ds_read_b32 v125, v7 offset:9140
	ds_read_b32 v126, v7 offset:9272
	ds_read_b32 v127, v7 offset:9404
	s_waitcnt lgkmcnt(0)
	v_cvt_pk_bf16_f32 v100, v120, v121
	v_cvt_pk_bf16_f32 v101, v122, v123
	v_cvt_pk_bf16_f32 v102, v124, v125
	v_cvt_pk_bf16_f32 v103, v126, v127
	global_store_dwordx4 v9, v[100:103], s[14:15] nt
	s_add_u32 s14, s14, s19
	s_addc_u32 s15, s15, 0
	ds_read_b32 v128, v7 offset:8512
	ds_read_b32 v129, v7 offset:8644
	ds_read_b32 v130, v7 offset:8776
	ds_read_b32 v131, v7 offset:8908
	ds_read_b32 v132, v7 offset:9040
	ds_read_b32 v133, v7 offset:9172
	ds_read_b32 v134, v7 offset:9304
	ds_read_b32 v135, v7 offset:9436
	s_waitcnt lgkmcnt(0)
	v_cvt_pk_bf16_f32 v104, v128, v129
	v_cvt_pk_bf16_f32 v105, v130, v131
	v_cvt_pk_bf16_f32 v106, v132, v133
	v_cvt_pk_bf16_f32 v107, v134, v135
	global_store_dwordx4 v9, v[104:107], s[14:15] nt
	s_add_u32 s14, s14, s19
	s_addc_u32 s15, s15, 0
	ds_read_b32 v136, v7 offset:8544
	ds_read_b32 v137, v7 offset:8676
	ds_read_b32 v138, v7 offset:8808
	ds_read_b32 v139, v7 offset:8940
	ds_read_b32 v140, v7 offset:9072
	ds_read_b32 v141, v7 offset:9204
	ds_read_b32 v142, v7 offset:9336
	ds_read_b32 v143, v7 offset:9468
	s_waitcnt lgkmcnt(0)
	v_cvt_pk_bf16_f32 v108, v136, v137
	v_cvt_pk_bf16_f32 v109, v138, v139
	v_cvt_pk_bf16_f32 v110, v140, v141
	v_cvt_pk_bf16_f32 v111, v142, v143
	global_store_dwordx4 v9, v[108:111], s[14:15] nt
	s_add_i32 s6, s23, s7
	s_cmpk_lt_u32 s6, 4224
	s_cbranch_scc1 .Lcvp10_item
	s_branch .Lcvp10_end

.Lcvp10_go_s:
	s_mul_i32 s1, s17, s12
	s_add_i32 s1, s1, s18
	s_lshl_b32 s1, s1, 2
	s_add_u32 s10, s10, s1
	s_addc_u32 s11, s11, 0
	v_mul_lo_u32 v8, v3, s12
	v_add_lshl_u32 v8, v8, v2, 2
	s_lshl_b32 s19, s12, 3
	global_load_dword v16, v8, s[10:11] nt
	s_add_u32 s10, s10, s19
	s_addc_u32 s11, s11, 0
	global_load_dword v17, v8, s[10:11] nt
	s_add_u32 s10, s10, s19
	s_addc_u32 s11, s11, 0
	global_load_dword v18, v8, s[10:11] nt
	s_add_u32 s10, s10, s19
	s_addc_u32 s11, s11, 0
	global_load_dword v19, v8, s[10:11] nt
	s_add_u32 s10, s10, s19
	s_addc_u32 s11, s11, 0
	global_load_dword v20, v8, s[10:11] nt
	s_add_u32 s10, s10, s19
	s_addc_u32 s11, s11, 0
	global_load_dword v21, v8, s[10:11] nt
	s_add_u32 s10, s10, s19
	s_addc_u32 s11, s11, 0
	global_load_dword v22, v8, s[10:11] nt
	s_add_u32 s10, s10, s19
	s_addc_u32 s11, s11, 0
	global_load_dword v23, v8, s[10:11] nt
	s_add_u32 s10, s10, s19
	s_addc_u32 s11, s11, 0
	global_load_dword v24, v8, s[10:11] nt
	s_add_u32 s10, s10, s19
	s_addc_u32 s11, s11, 0
	global_load_dword v25, v8, s[10:11] nt
	s_add_u32 s10, s10, s19
	s_addc_u32 s11, s11, 0
	global_load_dword v26, v8, s[10:11] nt
	s_add_u32 s10, s10, s19
	s_addc_u32 s11, s11, 0
	global_load_dword v27, v8, s[10:11] nt
	s_add_u32 s10, s10, s19
	s_addc_u32 s11, s11, 0
	global_load_dword v28, v8, s[10:11] nt
	s_add_u32 s10, s10, s19
	s_addc_u32 s11, s11, 0
	global_load_dword v29, v8, s[10:11] nt
	s_add_u32 s10, s10, s19
	s_addc_u32 s11, s11, 0
	global_load_dword v30, v8, s[10:11] nt
	s_add_u32 s10, s10, s19
	s_addc_u32 s11, s11, 0
	global_load_dword v31, v8, s[10:11] nt
	s_add_u32 s10, s10, s19
	s_addc_u32 s11, s11, 0
	global_load_dword v32, v8, s[10:11] nt
	s_add_u32 s10, s10, s19
	s_addc_u32 s11, s11, 0
	global_load_dword v33, v8, s[10:11] nt
	s_add_u32 s10, s10, s19
	s_addc_u32 s11, s11, 0
	global_load_dword v34, v8, s[10:11] nt
	s_add_u32 s10, s10, s19
	s_addc_u32 s11, s11, 0
	global_load_dword v35, v8, s[10:11] nt
	s_add_u32 s10, s10, s19
	s_addc_u32 s11, s11, 0
	global_load_dword v36, v8, s[10:11] nt
	s_add_u32 s10, s10, s19
	s_addc_u32 s11, s11, 0
	global_load_dword v37, v8, s[10:11] nt
	s_add_u32 s10, s10, s19
	s_addc_u32 s11, s11, 0
	global_load_dword v38, v8, s[10:11] nt
	s_add_u32 s10, s10, s19
	s_addc_u32 s11, s11, 0
	global_load_dword v39, v8, s[10:11] nt
	s_add_u32 s10, s10, s19
	s_addc_u32 s11, s11, 0
	global_load_dword v40, v8, s[10:11] nt
	s_add_u32 s10, s10, s19
	s_addc_u32 s11, s11, 0
	global_load_dword v41, v8, s[10:11] nt
	s_add_u32 s10, s10, s19
	s_addc_u32 s11, s11, 0
	global_load_dword v42, v8, s[10:11] nt
	s_add_u32 s10, s10, s19
	s_addc_u32 s11, s11, 0
	global_load_dword v43, v8, s[10:11] nt
	s_add_u32 s10, s10, s19
	s_addc_u32 s11, s11, 0
	global_load_dword v44, v8, s[10:11] nt
	s_add_u32 s10, s10, s19
	s_addc_u32 s11, s11, 0
	global_load_dword v45, v8, s[10:11] nt
	s_add_u32 s10, s10, s19
	s_addc_u32 s11, s11, 0
	global_load_dword v46, v8, s[10:11] nt
	s_add_u32 s10, s10, s19
	s_addc_u32 s11, s11, 0
	global_load_dword v47, v8, s[10:11] nt
	s_mul_i32 s1, s16, s13
	s_add_i32 s1, s1, s17
	s_lshl_b32 s1, s1, 1
	s_add_u32 s14, s14, s1
	s_addc_u32 s15, s15, 0
	s_waitcnt vmcnt(31)
	ds_write_b32 v4, v16 offset:0
	s_waitcnt vmcnt(30)
	ds_write_b32 v4, v17 offset:264
	s_waitcnt vmcnt(29)
	ds_write_b32 v4, v18 offset:528
	s_waitcnt vmcnt(28)
	ds_write_b32 v4, v19 offset:792
	s_waitcnt vmcnt(27)
	ds_write_b32 v4, v20 offset:1056
	s_waitcnt vmcnt(26)
	ds_write_b32 v4, v21 offset:1320
	s_waitcnt vmcnt(25)
	ds_write_b32 v4, v22 offset:1584
	s_waitcnt vmcnt(24)
	ds_write_b32 v4, v23 offset:1848
	s_waitcnt vmcnt(23)
	ds_write_b32 v4, v24 offset:2112
	s_waitcnt vmcnt(22)
	ds_write_b32 v4, v25 offset:2376
	s_waitcnt vmcnt(21)
	ds_write_b32 v4, v26 offset:2640
	s_waitcnt vmcnt(20)
	ds_write_b32 v4, v27 offset:2904
	s_waitcnt vmcnt(19)
	ds_write_b32 v4, v28 offset:3168
	s_waitcnt vmcnt(18)
	ds_write_b32 v4, v29 offset:3432
	s_waitcnt vmcnt(17)
	ds_write_b32 v4, v30 offset:3696
	s_waitcnt vmcnt(16)
	ds_write_b32 v4, v31 offset:3960
	s_waitcnt vmcnt(15)
	ds_write_b32 v4, v32 offset:4224
	s_waitcnt vmcnt(14)
	ds_write_b32 v4, v33 offset:4488
	s_waitcnt vmcnt(13)
	ds_write_b32 v4, v34 offset:4752
	s_waitcnt vmcnt(12)
	ds_write_b32 v4, v35 offset:5016
	s_waitcnt vmcnt(11)
	ds_write_b32 v4, v36 offset:5280
	s_waitcnt vmcnt(10)
	ds_write_b32 v4, v37 offset:5544
	s_waitcnt vmcnt(9)
	ds_write_b32 v4, v38 offset:5808
	s_waitcnt vmcnt(8)
	ds_write_b32 v4, v39 offset:6072
	s_waitcnt vmcnt(7)
	ds_write_b32 v4, v40 offset:6336
	s_waitcnt vmcnt(6)
	ds_write_b32 v4, v41 offset:6600
	s_waitcnt vmcnt(5)
	ds_write_b32 v4, v42 offset:6864
	s_waitcnt vmcnt(4)
	ds_write_b32 v4, v43 offset:7128
	s_waitcnt vmcnt(3)
	ds_write_b32 v4, v44 offset:7392
	s_waitcnt vmcnt(2)
	ds_write_b32 v4, v45 offset:7656
	s_waitcnt vmcnt(1)
	ds_write_b32 v4, v46 offset:7920
	s_waitcnt vmcnt(0)
	ds_write_b32 v4, v47 offset:8184
	s_waitcnt lgkmcnt(0)
	v_mul_lo_u32 v9, v6, s13
	v_lshl_add_u32 v96, v5, 3, v9
	v_lshlrev_b32_e32 v9, 1, v96
	s_lshl_b32 s19, s13, 4
	ds_read_b32 v112, v7 offset:0
	ds_read_b32 v113, v7 offset:132
	ds_read_b32 v114, v7 offset:264
	ds_read_b32 v115, v7 offset:396
	ds_read_b32 v116, v7 offset:528
	ds_read_b32 v117, v7 offset:660
	ds_read_b32 v118, v7 offset:792
	ds_read_b32 v119, v7 offset:924
	s_waitcnt lgkmcnt(0)
	v_cvt_pk_bf16_f32 v96, v112, v113
	v_cvt_pk_bf16_f32 v97, v114, v115
	v_cvt_pk_bf16_f32 v98, v116, v117
	v_cvt_pk_bf16_f32 v99, v118, v119
	global_store_dwordx4 v9, v[96:99], s[14:15] nt
	s_add_u32 s14, s14, s19
	s_addc_u32 s15, s15, 0
	ds_read_b32 v120, v7 offset:32
	ds_read_b32 v121, v7 offset:164
	ds_read_b32 v122, v7 offset:296
	ds_read_b32 v123, v7 offset:428
	ds_read_b32 v124, v7 offset:560
	ds_read_b32 v125, v7 offset:692
	ds_read_b32 v126, v7 offset:824
	ds_read_b32 v127, v7 offset:956
	s_waitcnt lgkmcnt(0)
	v_cvt_pk_bf16_f32 v100, v120, v121
	v_cvt_pk_bf16_f32 v101, v122, v123
	v_cvt_pk_bf16_f32 v102, v124, v125
	v_cvt_pk_bf16_f32 v103, v126, v127
	global_store_dwordx4 v9, v[100:103], s[14:15] nt
	s_add_u32 s14, s14, s19
	s_addc_u32 s15, s15, 0
	ds_read_b32 v128, v7 offset:64
	ds_read_b32 v129, v7 offset:196
	ds_read_b32 v130, v7 offset:328
	ds_read_b32 v131, v7 offset:460
	ds_read_b32 v132, v7 offset:592
	ds_read_b32 v133, v7 offset:724
	ds_read_b32 v134, v7 offset:856
	ds_read_b32 v135, v7 offset:988
	s_waitcnt lgkmcnt(0)
	v_cvt_pk_bf16_f32 v104, v128, v129
	v_cvt_pk_bf16_f32 v105, v130, v131
	v_cvt_pk_bf16_f32 v106, v132, v133
	v_cvt_pk_bf16_f32 v107, v134, v135
	global_store_dwordx4 v9, v[104:107], s[14:15] nt
	s_add_u32 s14, s14, s19
	s_addc_u32 s15, s15, 0
	ds_read_b32 v136, v7 offset:96
	ds_read_b32 v137, v7 offset:228
	ds_read_b32 v138, v7 offset:360
	ds_read_b32 v139, v7 offset:492
	ds_read_b32 v140, v7 offset:624
	ds_read_b32 v141, v7 offset:756
	ds_read_b32 v142, v7 offset:888
	ds_read_b32 v143, v7 offset:1020
	s_waitcnt lgkmcnt(0)
	v_cvt_pk_bf16_f32 v108, v136, v137
	v_cvt_pk_bf16_f32 v109, v138, v139
	v_cvt_pk_bf16_f32 v110, v140, v141
	v_cvt_pk_bf16_f32 v111, v142, v143
	global_store_dwordx4 v9, v[108:111], s[14:15] nt
.Lcvp10_end:
	s_waitcnt vmcnt(0)
	s_waitcnt vmcnt(0) lgkmcnt(0)
	s_barrier
	s_mov_b64 s[0:1], exec
	v_readlane_b32 s2, v255, 5
	v_readlane_b32 s3, v255, 6
	s_and_b64 s[2:3], s[0:1], s[2:3]
	s_mov_b64 exec, s[2:3]
	s_cbranch_execz .LBB0_1759
	s_add_u32 s2, s26, 0x4200
	s_addc_u32 s3, s27, 0
	s_add_i32 s4, 0, 0x24160
	v_mov_b32_e32 v1, s4
	s_waitcnt vmcnt(0) expcnt(0) lgkmcnt(0)
	ds_read_b32 v3, v1
	s_add_i32 s4, 0, 0x24164
	v_mov_b32_e32 v1, s4
	ds_read_b32 v1, v1
	s_waitcnt lgkmcnt(1)
	v_cmp_ne_u32_e32 vcc, 0, v3
	s_cbranch_vccnz .LBB0_1723
	s_add_u32 s4, s26, 0x4400
	s_addc_u32 s5, s27, 0
	s_add_u32 s6, s26, 0x4500
	s_addc_u32 s7, s27, 0
	s_add_u32 s8, s26, 0x4600
	s_addc_u32 s9, s27, 0
	s_add_u32 s10, s26, 0x4700
	s_addc_u32 s11, s27, 0
	s_add_u32 s12, s26, 0x4800
	s_addc_u32 s13, s27, 0
	s_add_u32 s14, s26, 0x4900
	s_addc_u32 s15, s27, 0
	s_add_u32 s16, s26, 0x4a00
	s_addc_u32 s17, s27, 0
	s_add_u32 s18, s26, 0x4b00
	s_addc_u32 s19, s27, 0
	s_add_u32 s20, s26, 0x4c00
	s_addc_u32 s21, s27, 0
	s_add_u32 s22, s26, 0x4d00
	s_addc_u32 s23, s27, 0
	s_add_u32 s30, s26, 0x4e00
	s_addc_u32 s31, s27, 0
	s_add_u32 s34, s26, 0x4f00
	s_addc_u32 s35, s27, 0
	v_readlane_b32 s40, v255, 0
	s_add_u32 s36, s26, 0x5000
	v_readlane_b32 s41, v255, 1
	s_addc_u32 s37, s27, 0
	s_load_dwordx2 s[28:29], s[40:41], 0x4
	s_add_u32 s38, s26, 0x5100
	s_addc_u32 s39, s27, 0
	s_add_u32 s40, s26, 0x5200
	s_addc_u32 s41, s27, 0
	s_add_u32 s42, s26, 0x5300
	s_waitcnt lgkmcnt(0)
	s_mul_i32 s25, s28, s33
	s_addc_u32 s43, s27, 0
	s_mul_i32 s25, s25, s29
	s_mov_b32 s28, 1
	v_mov_b32_e32 v17, 0
	s_branch .LBB0_1711
